# attention unit epilogue de-serialized: sub-LN rows batched (5 bpermute round trips instead of 80, f32 rsq), gated conv item loads issued up front
# speedup vs baseline: 1.0090x; 1.0090x over previous
; template <bool FIXED> __device__ __forceinline__ void attn_unit(int b, int h, int qb, const bf16* __restrict__ P, bf16* __restrict__ MIX, const float* __restrict__ BT, const float* __restrict__ subg, ...
;     ...
;   if (m == 0) {
;     bf16* Ow = MIX + (rowbase + qw0) * DMODEL + h * 128 + r32;
;     float gsub[4];
; #pragma unroll
;     for (int d0 = 0; d0 < 4; ++d0) gsub[d0] = subg[d0 * 32 + r32] * post;
; #pragma unroll
;     for (int r = 0; r < 16; ++r) { float y[4]; float ss = 0.f;
; #pragma unroll
;       for (int d0 = 0; d0 < 4; ++d0) { y[d0] = o[d0][r] * rli[r] - xch[(d0 * 16 + r) * 64]; ss += y[d0] * y[d0]; }
;       ss += __shfl_xor(ss, 1); ss += __shfl_xor(ss, 2); ss += __shfl_xor(ss, 4); ss += __shfl_xor(ss, 8); ss += __shfl_xor(ss, 16);
.LBB0_328:
	s_cmpk_gt_u32 s25, 0xff
	s_waitcnt lgkmcnt(0)
	s_barrier
	s_cbranch_scc1 .LBB0_330
	v_lshlrev_b32_e32 v65, 2, v134
	global_load_dword v69, v65, s[50:51]
	global_load_dword v67, v65, s[50:51] offset:128
	global_load_dword v68, v65, s[50:51] offset:256
	global_load_dword v70, v65, s[50:51] offset:384
	ds_read2st64_b32 v[88:89], v72 offset1:1
	ds_read2st64_b32 v[90:91], v72 offset0:2 offset1:3
	ds_read2st64_b32 v[92:93], v72 offset0:4 offset1:5
	ds_read2st64_b32 v[94:95], v72 offset0:6 offset1:7
	ds_read2st64_b32 v[96:97], v72 offset0:8 offset1:9
	ds_read2st64_b32 v[98:99], v72 offset0:10 offset1:11
	ds_read2st64_b32 v[100:101], v72 offset0:12 offset1:13
	ds_read2st64_b32 v[102:103], v72 offset0:14 offset1:15
	ds_read2st64_b32 v[104:105], v72 offset0:16 offset1:17
	ds_read2st64_b32 v[106:107], v72 offset0:18 offset1:19
	ds_read2st64_b32 v[108:109], v72 offset0:20 offset1:21
	ds_read2st64_b32 v[110:111], v72 offset0:22 offset1:23
	ds_read2st64_b32 v[112:113], v72 offset0:24 offset1:25
	ds_read2st64_b32 v[114:115], v72 offset0:26 offset1:27
	ds_read2st64_b32 v[116:117], v72 offset0:28 offset1:29
	ds_read2st64_b32 v[118:119], v72 offset0:30 offset1:31
	ds_read2st64_b32 v[120:121], v72 offset0:32 offset1:33
	ds_read2st64_b32 v[122:123], v72 offset0:34 offset1:35
	ds_read2st64_b32 v[124:125], v72 offset0:36 offset1:37
	ds_read2st64_b32 v[126:127], v72 offset0:38 offset1:39
	ds_read2st64_b32 v[198:199], v72 offset0:40 offset1:41
	ds_read2st64_b32 v[200:201], v72 offset0:42 offset1:43
	ds_read2st64_b32 v[202:203], v72 offset0:44 offset1:45
	ds_read2st64_b32 v[204:205], v72 offset0:46 offset1:47
	ds_read2st64_b32 v[206:207], v72 offset0:48 offset1:49
	ds_read2st64_b32 v[208:209], v72 offset0:50 offset1:51
	ds_read2st64_b32 v[210:211], v72 offset0:52 offset1:53
	ds_read2st64_b32 v[212:213], v72 offset0:54 offset1:55
	ds_read2st64_b32 v[214:215], v72 offset0:56 offset1:57
	ds_read2st64_b32 v[216:217], v72 offset0:58 offset1:59
	ds_read2st64_b32 v[218:219], v72 offset0:60 offset1:61
	ds_read2st64_b32 v[220:221], v72 offset0:62 offset1:63
	s_lshl_b64 s[0:1], s[22:23], 12
	s_add_u32 s0, s68, s0
	s_addc_u32 s1, s69, s1
	v_lshlrev_b32_e32 v144, 1, v134
	v_lshl_add_u64 v[86:87], s[0:1], 0, v[144:145]
	v_lshlrev_b32_e32 v144, 14, v167
	v_lshl_add_u64 v[86:87], v[86:87], 0, v[144:145]
	s_waitcnt lgkmcnt(15)
	v_fma_f32 v0, v0, v64, -v88
	v_fma_f32 v1, v1, v85, -v89
	v_fma_f32 v2, v2, v84, -v90
	v_fma_f32 v3, v3, v83, -v91
	v_fma_f32 v4, v4, v82, -v92
	v_fma_f32 v5, v5, v81, -v93
	v_fma_f32 v6, v6, v80, -v94
	v_fma_f32 v7, v7, v79, -v95
	v_fma_f32 v8, v8, v78, -v96
	v_fma_f32 v9, v9, v77, -v97
	v_fma_f32 v10, v10, v76, -v98
	v_fma_f32 v11, v11, v75, -v99
	v_fma_f32 v12, v12, v74, -v100
	v_fma_f32 v13, v13, v73, -v101
	v_fma_f32 v14, v14, v71, -v102
	v_fma_f32 v15, v15, v66, -v103
	s_waitcnt lgkmcnt(15)
	v_fma_f32 v16, v16, v64, -v104
	v_fma_f32 v17, v17, v85, -v105
	v_fma_f32 v18, v18, v84, -v106
	v_fma_f32 v19, v19, v83, -v107
	v_fma_f32 v20, v20, v82, -v108
	v_fma_f32 v21, v21, v81, -v109
	v_fma_f32 v22, v22, v80, -v110
	v_fma_f32 v23, v23, v79, -v111
	v_fma_f32 v24, v24, v78, -v112
	v_fma_f32 v25, v25, v77, -v113
	v_fma_f32 v26, v26, v76, -v114
	v_fma_f32 v27, v27, v75, -v115
	v_fma_f32 v28, v28, v74, -v116
	v_fma_f32 v29, v29, v73, -v117
	v_fma_f32 v30, v30, v71, -v118
	v_fma_f32 v31, v31, v66, -v119
	s_waitcnt lgkmcnt(8)
	v_fma_f32 v32, v32, v64, -v120
	v_fma_f32 v33, v33, v85, -v121
	v_fma_f32 v34, v34, v84, -v122
	v_fma_f32 v35, v35, v83, -v123
	v_fma_f32 v36, v36, v82, -v124
	v_fma_f32 v37, v37, v81, -v125
	v_fma_f32 v38, v38, v80, -v126
	v_fma_f32 v39, v39, v79, -v127
	v_fma_f32 v40, v40, v78, -v198
	v_fma_f32 v41, v41, v77, -v199
	v_fma_f32 v42, v42, v76, -v200
	v_fma_f32 v43, v43, v75, -v201
	v_fma_f32 v44, v44, v74, -v202
	v_fma_f32 v45, v45, v73, -v203
	v_fma_f32 v46, v46, v71, -v204
	v_fma_f32 v47, v47, v66, -v205
	s_waitcnt lgkmcnt(0)
	v_fma_f32 v48, v48, v64, -v206
	v_fma_f32 v49, v49, v85, -v207
	v_fma_f32 v50, v50, v84, -v208
	v_fma_f32 v51, v51, v83, -v209
	v_fma_f32 v52, v52, v82, -v210
	v_fma_f32 v53, v53, v81, -v211
	v_fma_f32 v54, v54, v80, -v212
	v_fma_f32 v55, v55, v79, -v213
	v_fma_f32 v56, v56, v78, -v214
	v_fma_f32 v57, v57, v77, -v215
	v_fma_f32 v58, v58, v76, -v216
	v_fma_f32 v59, v59, v75, -v217
	v_fma_f32 v60, v60, v74, -v218
	v_fma_f32 v61, v61, v73, -v219
	v_fma_f32 v62, v62, v71, -v220
	v_fma_f32 v63, v63, v66, -v221
	v_mul_f32_e32 v222, v16, v16
	v_mul_f32_e32 v223, v17, v17
	v_mul_f32_e32 v224, v18, v18
	v_mul_f32_e32 v225, v19, v19
	v_mul_f32_e32 v226, v20, v20
	v_mul_f32_e32 v227, v21, v21
	v_mul_f32_e32 v228, v22, v22
	v_mul_f32_e32 v229, v23, v23
	v_mul_f32_e32 v230, v24, v24
	v_mul_f32_e32 v231, v25, v25
	v_mul_f32_e32 v232, v26, v26
	v_mul_f32_e32 v233, v27, v27
	v_mul_f32_e32 v234, v28, v28
	v_mul_f32_e32 v235, v29, v29
	v_mul_f32_e32 v236, v30, v30
	v_mul_f32_e32 v237, v31, v31
	v_fmac_f32_e32 v222, v0, v0
	v_fmac_f32_e32 v223, v1, v1
	v_fmac_f32_e32 v224, v2, v2
	v_fmac_f32_e32 v225, v3, v3
	v_fmac_f32_e32 v226, v4, v4
	v_fmac_f32_e32 v227, v5, v5
	v_fmac_f32_e32 v228, v6, v6
	v_fmac_f32_e32 v229, v7, v7
	v_fmac_f32_e32 v230, v8, v8
	v_fmac_f32_e32 v231, v9, v9
	v_fmac_f32_e32 v232, v10, v10
	v_fmac_f32_e32 v233, v11, v11
	v_fmac_f32_e32 v234, v12, v12
	v_fmac_f32_e32 v235, v13, v13
	v_fmac_f32_e32 v236, v14, v14
	v_fmac_f32_e32 v237, v15, v15
	v_fmac_f32_e32 v222, v32, v32
	v_fmac_f32_e32 v223, v33, v33
	v_fmac_f32_e32 v224, v34, v34
	v_fmac_f32_e32 v225, v35, v35
	v_fmac_f32_e32 v226, v36, v36
	v_fmac_f32_e32 v227, v37, v37
	v_fmac_f32_e32 v228, v38, v38
	v_fmac_f32_e32 v229, v39, v39
	v_fmac_f32_e32 v230, v40, v40
	v_fmac_f32_e32 v231, v41, v41
	v_fmac_f32_e32 v232, v42, v42
	v_fmac_f32_e32 v233, v43, v43
	v_fmac_f32_e32 v234, v44, v44
	v_fmac_f32_e32 v235, v45, v45
	v_fmac_f32_e32 v236, v46, v46
	v_fmac_f32_e32 v237, v47, v47
	v_fmac_f32_e32 v222, v48, v48
	v_fmac_f32_e32 v223, v49, v49
	v_fmac_f32_e32 v224, v50, v50
	v_fmac_f32_e32 v225, v51, v51
	v_fmac_f32_e32 v226, v52, v52
	v_fmac_f32_e32 v227, v53, v53
	v_fmac_f32_e32 v228, v54, v54
	v_fmac_f32_e32 v229, v55, v55
	v_fmac_f32_e32 v230, v56, v56
	v_fmac_f32_e32 v231, v57, v57
	v_fmac_f32_e32 v232, v58, v58
	v_fmac_f32_e32 v233, v59, v59
	v_fmac_f32_e32 v234, v60, v60
	v_fmac_f32_e32 v235, v61, v61
	v_fmac_f32_e32 v236, v62, v62
	v_fmac_f32_e32 v237, v63, v63
	ds_bpermute_b32 v238, v135, v222
	ds_bpermute_b32 v239, v135, v223
	ds_bpermute_b32 v240, v135, v224
	ds_bpermute_b32 v241, v135, v225
	ds_bpermute_b32 v242, v135, v226
	ds_bpermute_b32 v243, v135, v227
	ds_bpermute_b32 v244, v135, v228
	ds_bpermute_b32 v245, v135, v229
	ds_bpermute_b32 v246, v135, v230
	ds_bpermute_b32 v247, v135, v231
	ds_bpermute_b32 v248, v135, v232
	ds_bpermute_b32 v249, v135, v233
	ds_bpermute_b32 v250, v135, v234
	ds_bpermute_b32 v251, v135, v235
	ds_bpermute_b32 v252, v135, v236
	ds_bpermute_b32 v253, v135, v237
	s_waitcnt lgkmcnt(15)
; template <bool FIXED> __device__ __forceinline__ void attn_unit(int b, int h, int qb, const bf16* __restrict__ P, bf16* __restrict__ MIX, const float* __restrict__ BT, const float* __restrict__ subg, ...
;     ...
;       ss += __shfl_xor(ss, 1); ss += __shfl_xor(ss, 2); ss += __shfl_xor(ss, 4); ss += __shfl_xor(ss, 8); ss += __shfl_xor(ss, 16);
	v_add_f32_e32 v222, v222, v238
	s_waitcnt lgkmcnt(14)
	v_add_f32_e32 v223, v223, v239
	s_waitcnt lgkmcnt(13)
	v_add_f32_e32 v224, v224, v240
	s_waitcnt lgkmcnt(12)
	v_add_f32_e32 v225, v225, v241
	s_waitcnt lgkmcnt(11)
	v_add_f32_e32 v226, v226, v242
	s_waitcnt lgkmcnt(10)
	v_add_f32_e32 v227, v227, v243
	s_waitcnt lgkmcnt(9)
	v_add_f32_e32 v228, v228, v244
	s_waitcnt lgkmcnt(8)
	v_add_f32_e32 v229, v229, v245
	s_waitcnt lgkmcnt(7)
	v_add_f32_e32 v230, v230, v246
	s_waitcnt lgkmcnt(6)
	v_add_f32_e32 v231, v231, v247
	s_waitcnt lgkmcnt(5)
	v_add_f32_e32 v232, v232, v248
	s_waitcnt lgkmcnt(4)
	v_add_f32_e32 v233, v233, v249
	s_waitcnt lgkmcnt(3)
	v_add_f32_e32 v234, v234, v250
	s_waitcnt lgkmcnt(2)
	v_add_f32_e32 v235, v235, v251
	s_waitcnt lgkmcnt(1)
	v_add_f32_e32 v236, v236, v252
	s_waitcnt lgkmcnt(0)
	v_add_f32_e32 v237, v237, v253
	ds_bpermute_b32 v238, v142, v222
	ds_bpermute_b32 v239, v142, v223
	ds_bpermute_b32 v240, v142, v224
	ds_bpermute_b32 v241, v142, v225
	ds_bpermute_b32 v242, v142, v226
	ds_bpermute_b32 v243, v142, v227
	ds_bpermute_b32 v244, v142, v228
	ds_bpermute_b32 v245, v142, v229
	ds_bpermute_b32 v246, v142, v230
	ds_bpermute_b32 v247, v142, v231
	ds_bpermute_b32 v248, v142, v232
	ds_bpermute_b32 v249, v142, v233
	ds_bpermute_b32 v250, v142, v234
	ds_bpermute_b32 v251, v142, v235
	ds_bpermute_b32 v252, v142, v236
	ds_bpermute_b32 v253, v142, v237
	s_waitcnt lgkmcnt(15)
	v_add_f32_e32 v222, v222, v238
	s_waitcnt lgkmcnt(14)
	v_add_f32_e32 v223, v223, v239
	s_waitcnt lgkmcnt(13)
	v_add_f32_e32 v224, v224, v240
	s_waitcnt lgkmcnt(12)
	v_add_f32_e32 v225, v225, v241
	s_waitcnt lgkmcnt(11)
	v_add_f32_e32 v226, v226, v242
	s_waitcnt lgkmcnt(10)
	v_add_f32_e32 v227, v227, v243
	s_waitcnt lgkmcnt(9)
	v_add_f32_e32 v228, v228, v244
	s_waitcnt lgkmcnt(8)
	v_add_f32_e32 v229, v229, v245
	s_waitcnt lgkmcnt(7)
	v_add_f32_e32 v230, v230, v246
	s_waitcnt lgkmcnt(6)
	v_add_f32_e32 v231, v231, v247
	s_waitcnt lgkmcnt(5)
	v_add_f32_e32 v232, v232, v248
	s_waitcnt lgkmcnt(4)
	v_add_f32_e32 v233, v233, v249
	s_waitcnt lgkmcnt(3)
	v_add_f32_e32 v234, v234, v250
	s_waitcnt lgkmcnt(2)
	v_add_f32_e32 v235, v235, v251
	s_waitcnt lgkmcnt(1)
	v_add_f32_e32 v236, v236, v252
	s_waitcnt lgkmcnt(0)
	v_add_f32_e32 v237, v237, v253
	ds_bpermute_b32 v238, v143, v222
	ds_bpermute_b32 v239, v143, v223
	ds_bpermute_b32 v240, v143, v224
	ds_bpermute_b32 v241, v143, v225
	ds_bpermute_b32 v242, v143, v226
	ds_bpermute_b32 v243, v143, v227
	ds_bpermute_b32 v244, v143, v228
	ds_bpermute_b32 v245, v143, v229
	ds_bpermute_b32 v246, v143, v230
	ds_bpermute_b32 v247, v143, v231
	ds_bpermute_b32 v248, v143, v232
	ds_bpermute_b32 v249, v143, v233
	ds_bpermute_b32 v250, v143, v234
	ds_bpermute_b32 v251, v143, v235
	ds_bpermute_b32 v252, v143, v236
	ds_bpermute_b32 v253, v143, v237
	s_waitcnt lgkmcnt(15)
	v_add_f32_e32 v222, v222, v238
	s_waitcnt lgkmcnt(14)
	v_add_f32_e32 v223, v223, v239
	s_waitcnt lgkmcnt(13)
	v_add_f32_e32 v224, v224, v240
	s_waitcnt lgkmcnt(12)
	v_add_f32_e32 v225, v225, v241
	s_waitcnt lgkmcnt(11)
	v_add_f32_e32 v226, v226, v242
	s_waitcnt lgkmcnt(10)
	v_add_f32_e32 v227, v227, v243
	s_waitcnt lgkmcnt(9)
	v_add_f32_e32 v228, v228, v244
	s_waitcnt lgkmcnt(8)
	v_add_f32_e32 v229, v229, v245
	s_waitcnt lgkmcnt(7)
	v_add_f32_e32 v230, v230, v246
	s_waitcnt lgkmcnt(6)
	v_add_f32_e32 v231, v231, v247
	s_waitcnt lgkmcnt(5)
	v_add_f32_e32 v232, v232, v248
	s_waitcnt lgkmcnt(4)
	v_add_f32_e32 v233, v233, v249
	s_waitcnt lgkmcnt(3)
	v_add_f32_e32 v234, v234, v250
	s_waitcnt lgkmcnt(2)
	v_add_f32_e32 v235, v235, v251
	s_waitcnt lgkmcnt(1)
	v_add_f32_e32 v236, v236, v252
	s_waitcnt lgkmcnt(0)
	v_add_f32_e32 v237, v237, v253
	ds_bpermute_b32 v238, v160, v222
	ds_bpermute_b32 v239, v160, v223
	ds_bpermute_b32 v240, v160, v224
	ds_bpermute_b32 v241, v160, v225
	ds_bpermute_b32 v242, v160, v226
	ds_bpermute_b32 v243, v160, v227
	ds_bpermute_b32 v244, v160, v228
	ds_bpermute_b32 v245, v160, v229
	ds_bpermute_b32 v246, v160, v230
	ds_bpermute_b32 v247, v160, v231
	ds_bpermute_b32 v248, v160, v232
	ds_bpermute_b32 v249, v160, v233
	ds_bpermute_b32 v250, v160, v234
	ds_bpermute_b32 v251, v160, v235
	ds_bpermute_b32 v252, v160, v236
	ds_bpermute_b32 v253, v160, v237
	s_waitcnt lgkmcnt(15)
	v_add_f32_e32 v222, v222, v238
	s_waitcnt lgkmcnt(14)
	v_add_f32_e32 v223, v223, v239
	s_waitcnt lgkmcnt(13)
	v_add_f32_e32 v224, v224, v240
	s_waitcnt lgkmcnt(12)
	v_add_f32_e32 v225, v225, v241
	s_waitcnt lgkmcnt(11)
	v_add_f32_e32 v226, v226, v242
	s_waitcnt lgkmcnt(10)
	v_add_f32_e32 v227, v227, v243
	s_waitcnt lgkmcnt(9)
	v_add_f32_e32 v228, v228, v244
	s_waitcnt lgkmcnt(8)
	v_add_f32_e32 v229, v229, v245
	s_waitcnt lgkmcnt(7)
	v_add_f32_e32 v230, v230, v246
	s_waitcnt lgkmcnt(6)
	v_add_f32_e32 v231, v231, v247
	s_waitcnt lgkmcnt(5)
	v_add_f32_e32 v232, v232, v248
	s_waitcnt lgkmcnt(4)
	v_add_f32_e32 v233, v233, v249
	s_waitcnt lgkmcnt(3)
	v_add_f32_e32 v234, v234, v250
	s_waitcnt lgkmcnt(2)
	v_add_f32_e32 v235, v235, v251
	s_waitcnt lgkmcnt(1)
	v_add_f32_e32 v236, v236, v252
	s_waitcnt lgkmcnt(0)
	v_add_f32_e32 v237, v237, v253
	ds_bpermute_b32 v238, v161, v222
	ds_bpermute_b32 v239, v161, v223
	ds_bpermute_b32 v240, v161, v224
	ds_bpermute_b32 v241, v161, v225
	ds_bpermute_b32 v242, v161, v226
	ds_bpermute_b32 v243, v161, v227
	ds_bpermute_b32 v244, v161, v228
	ds_bpermute_b32 v245, v161, v229
	ds_bpermute_b32 v246, v161, v230
	ds_bpermute_b32 v247, v161, v231
	ds_bpermute_b32 v248, v161, v232
	ds_bpermute_b32 v249, v161, v233
	ds_bpermute_b32 v250, v161, v234
	ds_bpermute_b32 v251, v161, v235
	ds_bpermute_b32 v252, v161, v236
	ds_bpermute_b32 v253, v161, v237
	s_waitcnt lgkmcnt(15)
; __device__ __forceinline__ int crow(int r, int hi) { return (r & 3) + 8 * (r >> 2) + 4 * hi; }
; template <bool FIXED> __device__ __forceinline__ void attn_unit(int b, int h, int qb, const bf16* __restrict__ P, bf16* __restrict__ MIX, const float* __restrict__ BT, const float* __restrict__ subg, ...
;     ...
;     for (int d0 = 0; d0 < 4; ++d0) gsub[d0] = subg[d0 * 32 + r32] * post;
; #pragma unroll
;     for (int r = 0; r < 16; ++r) { float y[4]; float ss = 0.f;
; #pragma unroll
;       for (int d0 = 0; d0 < 4; ++d0) { y[d0] = o[d0][r] * rli[r] - xch[(d0 * 16 + r) * 64]; ss += y[d0] * y[d0]; }
;       ss += __shfl_xor(ss, 1); ss += __shfl_xor(ss, 2); ss += __shfl_xor(ss, 4); ss += __shfl_xor(ss, 8); ss += __shfl_xor(ss, 16);
;       const float rs = 1.0f / sqrtf(ss * (1.0f / 128.0f) + 1e-6f);
; #pragma unroll
;       for (int d0 = 0; d0 < 4; ++d0) Ow[(long)crow(r, hi) * DMODEL + d0 * 32] = __float2bfloat16(y[d0] * rs * gsub[d0]); }
	v_add_f32_e32 v222, v222, v238
	s_waitcnt lgkmcnt(14)
	v_add_f32_e32 v223, v223, v239
	s_waitcnt lgkmcnt(13)
	v_add_f32_e32 v224, v224, v240
	s_waitcnt lgkmcnt(12)
	v_add_f32_e32 v225, v225, v241
	s_waitcnt lgkmcnt(11)
	v_add_f32_e32 v226, v226, v242
	s_waitcnt lgkmcnt(10)
	v_add_f32_e32 v227, v227, v243
	s_waitcnt lgkmcnt(9)
	v_add_f32_e32 v228, v228, v244
	s_waitcnt lgkmcnt(8)
	v_add_f32_e32 v229, v229, v245
	s_waitcnt lgkmcnt(7)
	v_add_f32_e32 v230, v230, v246
	s_waitcnt lgkmcnt(6)
	v_add_f32_e32 v231, v231, v247
	s_waitcnt lgkmcnt(5)
	v_add_f32_e32 v232, v232, v248
	s_waitcnt lgkmcnt(4)
	v_add_f32_e32 v233, v233, v249
	s_waitcnt lgkmcnt(3)
	v_add_f32_e32 v234, v234, v250
	s_waitcnt lgkmcnt(2)
	v_add_f32_e32 v235, v235, v251
	s_waitcnt lgkmcnt(1)
	v_add_f32_e32 v236, v236, v252
	s_waitcnt lgkmcnt(0)
	v_add_f32_e32 v237, v237, v253
	s_waitcnt vmcnt(0)
	v_mul_f32_e32 v69, v165, v69
	v_mul_f32_e32 v67, v165, v67
	v_mul_f32_e32 v68, v165, v68
	v_mul_f32_e32 v70, v165, v70
	v_fmamk_f32 v222, v222, 0x3c000000, v186
	v_rsq_f32_e32 v222, v222
	v_fmamk_f32 v223, v223, 0x3c000000, v186
	v_rsq_f32_e32 v223, v223
	v_fmamk_f32 v224, v224, 0x3c000000, v186
	v_rsq_f32_e32 v224, v224
	v_fmamk_f32 v225, v225, 0x3c000000, v186
	v_rsq_f32_e32 v225, v225
	v_fmamk_f32 v226, v226, 0x3c000000, v186
	v_rsq_f32_e32 v226, v226
	v_fmamk_f32 v227, v227, 0x3c000000, v186
	v_rsq_f32_e32 v227, v227
	v_fmamk_f32 v228, v228, 0x3c000000, v186
	v_rsq_f32_e32 v228, v228
	v_fmamk_f32 v229, v229, 0x3c000000, v186
	v_rsq_f32_e32 v229, v229
	v_fmamk_f32 v230, v230, 0x3c000000, v186
	v_rsq_f32_e32 v230, v230
	v_fmamk_f32 v231, v231, 0x3c000000, v186
	v_rsq_f32_e32 v231, v231
	v_fmamk_f32 v232, v232, 0x3c000000, v186
	v_rsq_f32_e32 v232, v232
	v_fmamk_f32 v233, v233, 0x3c000000, v186
	v_rsq_f32_e32 v233, v233
	v_fmamk_f32 v234, v234, 0x3c000000, v186
	v_rsq_f32_e32 v234, v234
	v_fmamk_f32 v235, v235, 0x3c000000, v186
	v_rsq_f32_e32 v235, v235
	v_fmamk_f32 v236, v236, 0x3c000000, v186
	v_rsq_f32_e32 v236, v236
	v_fmamk_f32 v237, v237, 0x3c000000, v186
	v_rsq_f32_e32 v237, v237
	v_mov_b32_e32 v88, v86
	v_mov_b32_e32 v89, v87
	v_add_co_u32_e32 v90, vcc, 0x1000, v86
	v_addc_co_u32_e32 v91, vcc, 0, v87, vcc
	v_add_co_u32_e32 v92, vcc, 0x2000, v86
	v_addc_co_u32_e32 v93, vcc, 0, v87, vcc
	v_add_co_u32_e32 v94, vcc, 0x3000, v86
	v_addc_co_u32_e32 v95, vcc, 0, v87, vcc
	v_add_co_u32_e32 v96, vcc, 0x8000, v86
	v_addc_co_u32_e32 v97, vcc, 0, v87, vcc
	v_add_co_u32_e32 v98, vcc, 0x9000, v86
	v_addc_co_u32_e32 v99, vcc, 0, v87, vcc
	v_add_co_u32_e32 v100, vcc, 0xa000, v86
	v_addc_co_u32_e32 v101, vcc, 0, v87, vcc
	v_add_co_u32_e32 v102, vcc, 0xb000, v86
	v_addc_co_u32_e32 v103, vcc, 0, v87, vcc
	v_add_co_u32_e32 v104, vcc, 0x10000, v86
	v_addc_co_u32_e32 v105, vcc, 0, v87, vcc
	v_add_co_u32_e32 v106, vcc, 0x11000, v86
	v_addc_co_u32_e32 v107, vcc, 0, v87, vcc
	v_add_co_u32_e32 v108, vcc, 0x12000, v86
	v_addc_co_u32_e32 v109, vcc, 0, v87, vcc
	v_add_co_u32_e32 v110, vcc, 0x13000, v86
	v_addc_co_u32_e32 v111, vcc, 0, v87, vcc
	v_add_co_u32_e32 v112, vcc, 0x18000, v86
	v_addc_co_u32_e32 v113, vcc, 0, v87, vcc
	v_add_co_u32_e32 v114, vcc, 0x19000, v86
	v_addc_co_u32_e32 v115, vcc, 0, v87, vcc
	v_add_co_u32_e32 v116, vcc, 0x1a000, v86
	v_addc_co_u32_e32 v117, vcc, 0, v87, vcc
	v_add_co_u32_e32 v118, vcc, 0x1b000, v86
	v_addc_co_u32_e32 v119, vcc, 0, v87, vcc
	v_mul_f32_e32 v120, v0, v222
	v_mul_f32_e32 v120, v69, v120
	v_cvt_pk_bf16_f32 v120, v120, s0
	global_store_short v[88:89], v120, off
	v_mul_f32_e32 v121, v16, v222
	v_mul_f32_e32 v121, v67, v121
	v_cvt_pk_bf16_f32 v121, v121, s0
	global_store_short v[88:89], v121, off offset:64
	v_mul_f32_e32 v122, v32, v222
	v_mul_f32_e32 v122, v68, v122
	v_cvt_pk_bf16_f32 v122, v122, s0
	global_store_short v[88:89], v122, off offset:128
	v_mul_f32_e32 v123, v48, v222
	v_mul_f32_e32 v123, v70, v123
	v_cvt_pk_bf16_f32 v123, v123, s0
	global_store_short v[88:89], v123, off offset:192
	v_mul_f32_e32 v124, v1, v223
	v_mul_f32_e32 v124, v69, v124
	v_cvt_pk_bf16_f32 v124, v124, s0
	global_store_short v[90:91], v124, off
	v_mul_f32_e32 v125, v17, v223
	v_mul_f32_e32 v125, v67, v125
	v_cvt_pk_bf16_f32 v125, v125, s0
	global_store_short v[90:91], v125, off offset:64
	v_mul_f32_e32 v126, v33, v223
	v_mul_f32_e32 v126, v68, v126
	v_cvt_pk_bf16_f32 v126, v126, s0
	global_store_short v[90:91], v126, off offset:128
	v_mul_f32_e32 v127, v49, v223
	v_mul_f32_e32 v127, v70, v127
	v_cvt_pk_bf16_f32 v127, v127, s0
	global_store_short v[90:91], v127, off offset:192
	v_mul_f32_e32 v120, v2, v224
	v_mul_f32_e32 v120, v69, v120
	v_cvt_pk_bf16_f32 v120, v120, s0
	global_store_short v[92:93], v120, off
	v_mul_f32_e32 v121, v18, v224
	v_mul_f32_e32 v121, v67, v121
	v_cvt_pk_bf16_f32 v121, v121, s0
	global_store_short v[92:93], v121, off offset:64
	v_mul_f32_e32 v122, v34, v224
	v_mul_f32_e32 v122, v68, v122
	v_cvt_pk_bf16_f32 v122, v122, s0
	global_store_short v[92:93], v122, off offset:128
	v_mul_f32_e32 v123, v50, v224
	v_mul_f32_e32 v123, v70, v123
	v_cvt_pk_bf16_f32 v123, v123, s0
	global_store_short v[92:93], v123, off offset:192
	v_mul_f32_e32 v124, v3, v225
	v_mul_f32_e32 v124, v69, v124
	v_cvt_pk_bf16_f32 v124, v124, s0
	global_store_short v[94:95], v124, off
	v_mul_f32_e32 v125, v19, v225
	v_mul_f32_e32 v125, v67, v125
	v_cvt_pk_bf16_f32 v125, v125, s0
	global_store_short v[94:95], v125, off offset:64
	v_mul_f32_e32 v126, v35, v225
	v_mul_f32_e32 v126, v68, v126
	v_cvt_pk_bf16_f32 v126, v126, s0
	global_store_short v[94:95], v126, off offset:128
	v_mul_f32_e32 v127, v51, v225
	v_mul_f32_e32 v127, v70, v127
	v_cvt_pk_bf16_f32 v127, v127, s0
; __device__ __forceinline__ int crow(int r, int hi) { return (r & 3) + 8 * (r >> 2) + 4 * hi; }
; template <bool FIXED> __device__ __forceinline__ void attn_unit(int b, int h, int qb, const bf16* __restrict__ P, bf16* __restrict__ MIX, const float* __restrict__ BT, const float* __restrict__ subg, ...
;     ...
;       for (int d0 = 0; d0 < 4; ++d0) Ow[(long)crow(r, hi) * DMODEL + d0 * 32] = __float2bfloat16(y[d0] * rs * gsub[d0]); }
	global_store_short v[94:95], v127, off offset:192
	v_mul_f32_e32 v120, v4, v226
	v_mul_f32_e32 v120, v69, v120
	v_cvt_pk_bf16_f32 v120, v120, s0
	global_store_short v[96:97], v120, off
	v_mul_f32_e32 v121, v20, v226
	v_mul_f32_e32 v121, v67, v121
	v_cvt_pk_bf16_f32 v121, v121, s0
	global_store_short v[96:97], v121, off offset:64
	v_mul_f32_e32 v122, v36, v226
	v_mul_f32_e32 v122, v68, v122
	v_cvt_pk_bf16_f32 v122, v122, s0
	global_store_short v[96:97], v122, off offset:128
	v_mul_f32_e32 v123, v52, v226
	v_mul_f32_e32 v123, v70, v123
	v_cvt_pk_bf16_f32 v123, v123, s0
	global_store_short v[96:97], v123, off offset:192
	v_mul_f32_e32 v124, v5, v227
	v_mul_f32_e32 v124, v69, v124
	v_cvt_pk_bf16_f32 v124, v124, s0
	global_store_short v[98:99], v124, off
	v_mul_f32_e32 v125, v21, v227
	v_mul_f32_e32 v125, v67, v125
	v_cvt_pk_bf16_f32 v125, v125, s0
	global_store_short v[98:99], v125, off offset:64
	v_mul_f32_e32 v126, v37, v227
	v_mul_f32_e32 v126, v68, v126
	v_cvt_pk_bf16_f32 v126, v126, s0
	global_store_short v[98:99], v126, off offset:128
	v_mul_f32_e32 v127, v53, v227
	v_mul_f32_e32 v127, v70, v127
	v_cvt_pk_bf16_f32 v127, v127, s0
	global_store_short v[98:99], v127, off offset:192
	v_mul_f32_e32 v120, v6, v228
	v_mul_f32_e32 v120, v69, v120
	v_cvt_pk_bf16_f32 v120, v120, s0
	global_store_short v[100:101], v120, off
	v_mul_f32_e32 v121, v22, v228
	v_mul_f32_e32 v121, v67, v121
	v_cvt_pk_bf16_f32 v121, v121, s0
	global_store_short v[100:101], v121, off offset:64
	v_mul_f32_e32 v122, v38, v228
	v_mul_f32_e32 v122, v68, v122
	v_cvt_pk_bf16_f32 v122, v122, s0
	global_store_short v[100:101], v122, off offset:128
	v_mul_f32_e32 v123, v54, v228
	v_mul_f32_e32 v123, v70, v123
	v_cvt_pk_bf16_f32 v123, v123, s0
	global_store_short v[100:101], v123, off offset:192
	v_mul_f32_e32 v124, v7, v229
	v_mul_f32_e32 v124, v69, v124
	v_cvt_pk_bf16_f32 v124, v124, s0
	global_store_short v[102:103], v124, off
	v_mul_f32_e32 v125, v23, v229
	v_mul_f32_e32 v125, v67, v125
	v_cvt_pk_bf16_f32 v125, v125, s0
	global_store_short v[102:103], v125, off offset:64
	v_mul_f32_e32 v126, v39, v229
	v_mul_f32_e32 v126, v68, v126
	v_cvt_pk_bf16_f32 v126, v126, s0
	global_store_short v[102:103], v126, off offset:128
	v_mul_f32_e32 v127, v55, v229
	v_mul_f32_e32 v127, v70, v127
	v_cvt_pk_bf16_f32 v127, v127, s0
	global_store_short v[102:103], v127, off offset:192
	v_mul_f32_e32 v120, v8, v230
	v_mul_f32_e32 v120, v69, v120
	v_cvt_pk_bf16_f32 v120, v120, s0
	global_store_short v[104:105], v120, off
	v_mul_f32_e32 v121, v24, v230
	v_mul_f32_e32 v121, v67, v121
	v_cvt_pk_bf16_f32 v121, v121, s0
	global_store_short v[104:105], v121, off offset:64
	v_mul_f32_e32 v122, v40, v230
	v_mul_f32_e32 v122, v68, v122
	v_cvt_pk_bf16_f32 v122, v122, s0
	global_store_short v[104:105], v122, off offset:128
	v_mul_f32_e32 v123, v56, v230
	v_mul_f32_e32 v123, v70, v123
	v_cvt_pk_bf16_f32 v123, v123, s0
	global_store_short v[104:105], v123, off offset:192
	v_mul_f32_e32 v124, v9, v231
	v_mul_f32_e32 v124, v69, v124
	v_cvt_pk_bf16_f32 v124, v124, s0
	global_store_short v[106:107], v124, off
	v_mul_f32_e32 v125, v25, v231
	v_mul_f32_e32 v125, v67, v125
	v_cvt_pk_bf16_f32 v125, v125, s0
	global_store_short v[106:107], v125, off offset:64
	v_mul_f32_e32 v126, v41, v231
	v_mul_f32_e32 v126, v68, v126
	v_cvt_pk_bf16_f32 v126, v126, s0
	global_store_short v[106:107], v126, off offset:128
	v_mul_f32_e32 v127, v57, v231
	v_mul_f32_e32 v127, v70, v127
	v_cvt_pk_bf16_f32 v127, v127, s0
	global_store_short v[106:107], v127, off offset:192
	v_mul_f32_e32 v120, v10, v232
	v_mul_f32_e32 v120, v69, v120
	v_cvt_pk_bf16_f32 v120, v120, s0
	global_store_short v[108:109], v120, off
	v_mul_f32_e32 v121, v26, v232
	v_mul_f32_e32 v121, v67, v121
	v_cvt_pk_bf16_f32 v121, v121, s0
	global_store_short v[108:109], v121, off offset:64
	v_mul_f32_e32 v122, v42, v232
	v_mul_f32_e32 v122, v68, v122
	v_cvt_pk_bf16_f32 v122, v122, s0
	global_store_short v[108:109], v122, off offset:128
	v_mul_f32_e32 v123, v58, v232
	v_mul_f32_e32 v123, v70, v123
	v_cvt_pk_bf16_f32 v123, v123, s0
	global_store_short v[108:109], v123, off offset:192
	v_mul_f32_e32 v124, v11, v233
	v_mul_f32_e32 v124, v69, v124
	v_cvt_pk_bf16_f32 v124, v124, s0
	global_store_short v[110:111], v124, off
	v_mul_f32_e32 v125, v27, v233
	v_mul_f32_e32 v125, v67, v125
	v_cvt_pk_bf16_f32 v125, v125, s0
	global_store_short v[110:111], v125, off offset:64
	v_mul_f32_e32 v126, v43, v233
	v_mul_f32_e32 v126, v68, v126
	v_cvt_pk_bf16_f32 v126, v126, s0
	global_store_short v[110:111], v126, off offset:128
	v_mul_f32_e32 v127, v59, v233
	v_mul_f32_e32 v127, v70, v127
	v_cvt_pk_bf16_f32 v127, v127, s0
	global_store_short v[110:111], v127, off offset:192
	v_mul_f32_e32 v120, v12, v234
	v_mul_f32_e32 v120, v69, v120
	v_cvt_pk_bf16_f32 v120, v120, s0
	global_store_short v[112:113], v120, off
	v_mul_f32_e32 v121, v28, v234
	v_mul_f32_e32 v121, v67, v121
	v_cvt_pk_bf16_f32 v121, v121, s0
	global_store_short v[112:113], v121, off offset:64
	v_mul_f32_e32 v122, v44, v234
	v_mul_f32_e32 v122, v68, v122
	v_cvt_pk_bf16_f32 v122, v122, s0
	global_store_short v[112:113], v122, off offset:128
	v_mul_f32_e32 v123, v60, v234
	v_mul_f32_e32 v123, v70, v123
	v_cvt_pk_bf16_f32 v123, v123, s0
	global_store_short v[112:113], v123, off offset:192
	v_mul_f32_e32 v124, v13, v235
	v_mul_f32_e32 v124, v69, v124
	v_cvt_pk_bf16_f32 v124, v124, s0
	global_store_short v[114:115], v124, off
	v_mul_f32_e32 v125, v29, v235
	v_mul_f32_e32 v125, v67, v125
	v_cvt_pk_bf16_f32 v125, v125, s0
	global_store_short v[114:115], v125, off offset:64
	v_mul_f32_e32 v126, v45, v235
	v_mul_f32_e32 v126, v68, v126
	v_cvt_pk_bf16_f32 v126, v126, s0
	global_store_short v[114:115], v126, off offset:128
	v_mul_f32_e32 v127, v61, v235
	v_mul_f32_e32 v127, v70, v127
	v_cvt_pk_bf16_f32 v127, v127, s0
	global_store_short v[114:115], v127, off offset:192
	v_mul_f32_e32 v120, v14, v236
	v_mul_f32_e32 v120, v69, v120
	v_cvt_pk_bf16_f32 v120, v120, s0
	global_store_short v[116:117], v120, off
	v_mul_f32_e32 v121, v30, v236
	v_mul_f32_e32 v121, v67, v121
	v_cvt_pk_bf16_f32 v121, v121, s0
	global_store_short v[116:117], v121, off offset:64
	v_mul_f32_e32 v122, v46, v236
	v_mul_f32_e32 v122, v68, v122
	v_cvt_pk_bf16_f32 v122, v122, s0
	global_store_short v[116:117], v122, off offset:128
	v_mul_f32_e32 v123, v62, v236
	v_mul_f32_e32 v123, v70, v123
	v_cvt_pk_bf16_f32 v123, v123, s0
	global_store_short v[116:117], v123, off offset:192
	v_mul_f32_e32 v124, v15, v237
	v_mul_f32_e32 v124, v69, v124
	v_cvt_pk_bf16_f32 v124, v124, s0
	global_store_short v[118:119], v124, off
	v_mul_f32_e32 v125, v31, v237
	v_mul_f32_e32 v125, v67, v125
	v_cvt_pk_bf16_f32 v125, v125, s0
	global_store_short v[118:119], v125, off offset:64
	v_mul_f32_e32 v126, v47, v237
	v_mul_f32_e32 v126, v68, v126
	v_cvt_pk_bf16_f32 v126, v126, s0
	global_store_short v[118:119], v126, off offset:128
	v_mul_f32_e32 v127, v63, v237
	v_mul_f32_e32 v127, v70, v127
	v_cvt_pk_bf16_f32 v127, v127, s0
	global_store_short v[118:119], v127, off offset:192
; __device__ __forceinline__ unsigned cvtpk(float lo, float hi) { unsigned r; asm volatile("v_cvt_pk_bf16_f32 %0, %1, %2" : "=v"(r) : "v"(lo), "v"(hi)); return r; }
; __device__ __forceinline__ void conv_item(const bf16* __restrict__ P, bf16* __restrict__ MIX, const float* __restrict__ cw, int it, int lane) {
;   const unsigned short* Pu = reinterpret_cast<const unsigned short*>(P); unsigned short* Mu = reinterpret_cast<unsigned short*>(MIX);
;   const int t0 = it * 4; const bool first = (t0 % SEQ) == 0;
; #pragma unroll
;   for (int j = 0; j < 2; ++j) { const int c0 = j * 512 + lane * 8;
;     float w0[8], w1[8], w2[8];
; #pragma unroll
;     for (int e = 0; e < 8; ++e) { w0[e] = cw[c0 + e]; w1[e] = cw[1024 + c0 + e]; w2[e] = cw[2048 + c0 + e]; }
;     float p[6][8];
; #pragma unroll
;     for (int k = 0; k < 6; ++k) { const int t = t0 - 2 + k;
;       if (k < 2 && first) {
; #pragma unroll
;         for (int e = 0; e < 8; ++e) p[k][e] = 0.f;
;       } else { const u32x4 gp = *(const u32x4*)(Pu + (size_t)t * PW + 4096 + c0);
; #pragma unroll
;         for (int e = 0; e < 4; ++e) { p[k][2 * e] = __uint_as_float(gp[e] << 16); p[k][2 * e + 1] = __uint_as_float(gp[e] & 0xffff0000u); } } }
; #pragma unroll
;     for (int i = 0; i < 4; ++i) { const u32x4 gb = *(const u32x4*)(Pu + (size_t)(t0 + i) * PW + 3072 + c0); float r[8];
; #pragma unroll
;       for (int e = 0; e < 4; ++e) { r[2 * e] = __uint_as_float(gb[e] << 16) * (w0[2 * e] * p[i][2 * e] + w1[2 * e] * p[i + 1][2 * e] + w2[2 * e] * p[i + 2][2 * e]);
;         r[2 * e + 1] = __uint_as_float(gb[e] & 0xffff0000u) * (w0[2 * e + 1] * p[i][2 * e + 1] + w1[2 * e + 1] * p[i + 1][2 * e + 1] + w2[2 * e + 1] * p[i + 2][2 * e + 1]); }
;       u32x4 o; o.x = cvtpk(r[0], r[1]); o.y = cvtpk(r[2], r[3]); o.z = cvtpk(r[4], r[5]); o.w = cvtpk(r[6], r[7]);
;       *(u32x4*)(Mu + (size_t)(t0 + i) * DMODEL + 1024 + c0) = o; } }
.LBB0_330:
	s_andn2_b64 vcc, exec, s[84:85]
	s_cbranch_vccnz .LBB0_340
	s_or_b32 s0, s24, s71
	s_lshl_b32 s80, s0, 2
	s_and_b32 s6, s0, 0x1ff
	s_cmp_eq_u32 s6, 0
	s_cselect_b32 s59, 0, -1
	s_add_i32 s60, s80, -2
	s_mul_hi_i32 s56, s60, 0x3000
	s_mulk_i32 s60, 0x3000
	s_add_u32 s22, s14, s60
	s_addc_u32 s23, s46, s56
	s_add_u32 s22, s22, 0x2000
	s_addc_u32 s23, s23, 0
	s_add_u32 s28, s22, 0x5800
	s_addc_u32 s29, s23, 0
	s_ashr_i32 s81, s80, 31
	s_lshl_b64 s[0:1], s[80:81], 12
	s_add_u32 s0, s42, s0
	s_addc_u32 s1, s43, s1
	v_lshlrev_b32_e32 v204, 2, v166
	v_lshlrev_b32_e32 v198, 1, v166
	v_add_u32_e32 v205, 0x1000, v204
	v_add_u32_e32 v206, 0x2000, v204
	v_add_u32_e32 v199, 0x3000, v198
	v_add_u32_e32 v200, 0x6000, v198
	v_add_u32_e32 v201, 0x9000, v198
	v_add_u32_e32 v202, 0xc000, v198
	v_add_u32_e32 v203, 0xf000, v198
	v_add_u32_e32 v207, 0x1000, v198
	v_add_u32_e32 v208, 0x2000, v198
	global_load_dwordx4 v[0:3], v204, s[52:53]
	global_load_dwordx4 v[4:7], v204, s[52:53] offset:16
	global_load_dwordx4 v[8:11], v205, s[52:53]
	global_load_dwordx4 v[12:15], v205, s[52:53] offset:16
	global_load_dwordx4 v[16:19], v206, s[52:53]
	global_load_dwordx4 v[20:23], v206, s[52:53] offset:16
	global_load_dwordx4 v[48:51], v198, s[22:23]
	global_load_dwordx4 v[52:55], v199, s[22:23]
	global_load_dwordx4 v[56:59], v200, s[22:23]
	global_load_dwordx4 v[60:63], v201, s[22:23]
	global_load_dwordx4 v[64:67], v202, s[22:23]
	global_load_dwordx4 v[68:71], v203, s[22:23]
	global_load_dwordx4 v[96:99], v198, s[28:29]
	global_load_dwordx4 v[100:103], v199, s[28:29]
	global_load_dwordx4 v[104:107], v200, s[28:29]
	global_load_dwordx4 v[108:111], v201, s[28:29]
	global_load_dwordx4 v[24:27], v204, s[52:53] offset:2048
	global_load_dwordx4 v[28:31], v204, s[52:53] offset:2064
	global_load_dwordx4 v[32:35], v205, s[52:53] offset:2048
	global_load_dwordx4 v[36:39], v205, s[52:53] offset:2064
	global_load_dwordx4 v[40:43], v206, s[52:53] offset:2048
	global_load_dwordx4 v[44:47], v206, s[52:53] offset:2064
	global_load_dwordx4 v[72:75], v198, s[22:23] offset:1024
	global_load_dwordx4 v[76:79], v199, s[22:23] offset:1024
	global_load_dwordx4 v[80:83], v200, s[22:23] offset:1024
	global_load_dwordx4 v[84:87], v201, s[22:23] offset:1024
	global_load_dwordx4 v[88:91], v202, s[22:23] offset:1024
	global_load_dwordx4 v[92:95], v203, s[22:23] offset:1024
	global_load_dwordx4 v[112:115], v198, s[28:29] offset:1024
	global_load_dwordx4 v[116:119], v199, s[28:29] offset:1024
	global_load_dwordx4 v[120:123], v200, s[28:29] offset:1024
	global_load_dwordx4 v[124:127], v201, s[28:29] offset:1024
	s_waitcnt vmcnt(16)
	v_and_b32_e32 v48, s59, v48
	v_and_b32_e32 v49, s59, v49
	v_and_b32_e32 v50, s59, v50
	v_and_b32_e32 v51, s59, v51
	v_and_b32_e32 v52, s59, v52
	v_and_b32_e32 v53, s59, v53
	v_and_b32_e32 v54, s59, v54
	v_and_b32_e32 v55, s59, v55
	v_lshlrev_b32_e32 v212, 16, v48
	v_and_b32_e32 v213, 0xffff0000, v48
	v_lshlrev_b32_e32 v214, 16, v52
	v_and_b32_e32 v215, 0xffff0000, v52
	v_lshlrev_b32_e32 v216, 16, v56
	v_and_b32_e32 v217, 0xffff0000, v56
	v_lshlrev_b32_e32 v218, 16, v60
	v_and_b32_e32 v219, 0xffff0000, v60
	v_lshlrev_b32_e32 v220, 16, v64
	v_and_b32_e32 v221, 0xffff0000, v64
	v_lshlrev_b32_e32 v222, 16, v68
	v_and_b32_e32 v223, 0xffff0000, v68
	v_lshlrev_b32_e32 v224, 16, v96
	v_and_b32_e32 v225, 0xffff0000, v96
	v_lshlrev_b32_e32 v226, 16, v100
	v_and_b32_e32 v227, 0xffff0000, v100
	v_lshlrev_b32_e32 v228, 16, v104
	v_and_b32_e32 v229, 0xffff0000, v104
	v_lshlrev_b32_e32 v230, 16, v108
	v_and_b32_e32 v231, 0xffff0000, v108
	v_pk_mul_f32 v[232:233], v[0:1], v[212:213]
	v_pk_mul_f32 v[234:235], v[0:1], v[214:215]
	v_pk_mul_f32 v[236:237], v[0:1], v[216:217]
	v_pk_mul_f32 v[238:239], v[0:1], v[218:219]
	v_pk_fma_f32 v[232:233], v[8:9], v[214:215], v[232:233]
	v_pk_fma_f32 v[234:235], v[8:9], v[216:217], v[234:235]
	v_pk_fma_f32 v[236:237], v[8:9], v[218:219], v[236:237]
	v_pk_fma_f32 v[238:239], v[8:9], v[220:221], v[238:239]
	v_pk_fma_f32 v[232:233], v[16:17], v[216:217], v[232:233]
	v_pk_fma_f32 v[234:235], v[16:17], v[218:219], v[234:235]
	v_pk_fma_f32 v[236:237], v[16:17], v[220:221], v[236:237]
	v_pk_fma_f32 v[238:239], v[16:17], v[222:223], v[238:239]
	v_pk_mul_f32 v[232:233], v[224:225], v[232:233]
	v_pk_mul_f32 v[234:235], v[226:227], v[234:235]
	v_pk_mul_f32 v[236:237], v[228:229], v[236:237]
	v_pk_mul_f32 v[238:239], v[230:231], v[238:239]
	v_cvt_pk_bf16_f32 v96, v232, v233
	v_cvt_pk_bf16_f32 v100, v234, v235
	v_cvt_pk_bf16_f32 v104, v236, v237
	v_cvt_pk_bf16_f32 v108, v238, v239
	v_lshlrev_b32_e32 v212, 16, v49
	v_and_b32_e32 v213, 0xffff0000, v49
	v_lshlrev_b32_e32 v214, 16, v53
	v_and_b32_e32 v215, 0xffff0000, v53
	v_lshlrev_b32_e32 v216, 16, v57
	v_and_b32_e32 v217, 0xffff0000, v57
	v_lshlrev_b32_e32 v218, 16, v61
	v_and_b32_e32 v219, 0xffff0000, v61
	v_lshlrev_b32_e32 v220, 16, v65
	v_and_b32_e32 v221, 0xffff0000, v65
	v_lshlrev_b32_e32 v222, 16, v69
	v_and_b32_e32 v223, 0xffff0000, v69
	v_lshlrev_b32_e32 v224, 16, v97
	v_and_b32_e32 v225, 0xffff0000, v97
	v_lshlrev_b32_e32 v226, 16, v101
	v_and_b32_e32 v227, 0xffff0000, v101
	v_lshlrev_b32_e32 v228, 16, v105
	v_and_b32_e32 v229, 0xffff0000, v105
	v_lshlrev_b32_e32 v230, 16, v109
	v_and_b32_e32 v231, 0xffff0000, v109
	v_pk_mul_f32 v[232:233], v[2:3], v[212:213]
	v_pk_mul_f32 v[234:235], v[2:3], v[214:215]
	v_pk_mul_f32 v[236:237], v[2:3], v[216:217]
	v_pk_mul_f32 v[238:239], v[2:3], v[218:219]
	v_pk_fma_f32 v[232:233], v[10:11], v[214:215], v[232:233]
	v_pk_fma_f32 v[234:235], v[10:11], v[216:217], v[234:235]
	v_pk_fma_f32 v[236:237], v[10:11], v[218:219], v[236:237]
	v_pk_fma_f32 v[238:239], v[10:11], v[220:221], v[238:239]
; __device__ __forceinline__ unsigned cvtpk(float lo, float hi) { unsigned r; asm volatile("v_cvt_pk_bf16_f32 %0, %1, %2" : "=v"(r) : "v"(lo), "v"(hi)); return r; }
; __device__ __forceinline__ void conv_item(const bf16* __restrict__ P, bf16* __restrict__ MIX, const float* __restrict__ cw, int it, int lane) {
;     ...
;     for (int i = 0; i < 4; ++i) { const u32x4 gb = *(const u32x4*)(Pu + (size_t)(t0 + i) * PW + 3072 + c0); float r[8];
; #pragma unroll
;       for (int e = 0; e < 4; ++e) { r[2 * e] = __uint_as_float(gb[e] << 16) * (w0[2 * e] * p[i][2 * e] + w1[2 * e] * p[i + 1][2 * e] + w2[2 * e] * p[i + 2][2 * e]);
;         r[2 * e + 1] = __uint_as_float(gb[e] & 0xffff0000u) * (w0[2 * e + 1] * p[i][2 * e + 1] + w1[2 * e + 1] * p[i + 1][2 * e + 1] + w2[2 * e + 1] * p[i + 2][2 * e + 1]); }
;       u32x4 o; o.x = cvtpk(r[0], r[1]); o.y = cvtpk(r[2], r[3]); o.z = cvtpk(r[4], r[5]); o.w = cvtpk(r[6], r[7]);
;       *(u32x4*)(Mu + (size_t)(t0 + i) * DMODEL + 1024 + c0) = o; } }
	v_pk_fma_f32 v[232:233], v[18:19], v[216:217], v[232:233]
	v_pk_fma_f32 v[234:235], v[18:19], v[218:219], v[234:235]
	v_pk_fma_f32 v[236:237], v[18:19], v[220:221], v[236:237]
	v_pk_fma_f32 v[238:239], v[18:19], v[222:223], v[238:239]
	v_pk_mul_f32 v[232:233], v[224:225], v[232:233]
	v_pk_mul_f32 v[234:235], v[226:227], v[234:235]
	v_pk_mul_f32 v[236:237], v[228:229], v[236:237]
	v_pk_mul_f32 v[238:239], v[230:231], v[238:239]
	v_cvt_pk_bf16_f32 v97, v232, v233
	v_cvt_pk_bf16_f32 v101, v234, v235
	v_cvt_pk_bf16_f32 v105, v236, v237
	v_cvt_pk_bf16_f32 v109, v238, v239
	v_lshlrev_b32_e32 v212, 16, v50
	v_and_b32_e32 v213, 0xffff0000, v50
	v_lshlrev_b32_e32 v214, 16, v54
	v_and_b32_e32 v215, 0xffff0000, v54
	v_lshlrev_b32_e32 v216, 16, v58
	v_and_b32_e32 v217, 0xffff0000, v58
	v_lshlrev_b32_e32 v218, 16, v62
	v_and_b32_e32 v219, 0xffff0000, v62
	v_lshlrev_b32_e32 v220, 16, v66
	v_and_b32_e32 v221, 0xffff0000, v66
	v_lshlrev_b32_e32 v222, 16, v70
	v_and_b32_e32 v223, 0xffff0000, v70
	v_lshlrev_b32_e32 v224, 16, v98
	v_and_b32_e32 v225, 0xffff0000, v98
	v_lshlrev_b32_e32 v226, 16, v102
	v_and_b32_e32 v227, 0xffff0000, v102
	v_lshlrev_b32_e32 v228, 16, v106
	v_and_b32_e32 v229, 0xffff0000, v106
	v_lshlrev_b32_e32 v230, 16, v110
	v_and_b32_e32 v231, 0xffff0000, v110
	v_pk_mul_f32 v[232:233], v[4:5], v[212:213]
	v_pk_mul_f32 v[234:235], v[4:5], v[214:215]
	v_pk_mul_f32 v[236:237], v[4:5], v[216:217]
	v_pk_mul_f32 v[238:239], v[4:5], v[218:219]
	v_pk_fma_f32 v[232:233], v[12:13], v[214:215], v[232:233]
	v_pk_fma_f32 v[234:235], v[12:13], v[216:217], v[234:235]
	v_pk_fma_f32 v[236:237], v[12:13], v[218:219], v[236:237]
	v_pk_fma_f32 v[238:239], v[12:13], v[220:221], v[238:239]
	v_pk_fma_f32 v[232:233], v[20:21], v[216:217], v[232:233]
	v_pk_fma_f32 v[234:235], v[20:21], v[218:219], v[234:235]
	v_pk_fma_f32 v[236:237], v[20:21], v[220:221], v[236:237]
	v_pk_fma_f32 v[238:239], v[20:21], v[222:223], v[238:239]
	v_pk_mul_f32 v[232:233], v[224:225], v[232:233]
	v_pk_mul_f32 v[234:235], v[226:227], v[234:235]
	v_pk_mul_f32 v[236:237], v[228:229], v[236:237]
	v_pk_mul_f32 v[238:239], v[230:231], v[238:239]
	v_cvt_pk_bf16_f32 v98, v232, v233
	v_cvt_pk_bf16_f32 v102, v234, v235
	v_cvt_pk_bf16_f32 v106, v236, v237
	v_cvt_pk_bf16_f32 v110, v238, v239
	v_lshlrev_b32_e32 v212, 16, v51
	v_and_b32_e32 v213, 0xffff0000, v51
	v_lshlrev_b32_e32 v214, 16, v55
	v_and_b32_e32 v215, 0xffff0000, v55
	v_lshlrev_b32_e32 v216, 16, v59
	v_and_b32_e32 v217, 0xffff0000, v59
	v_lshlrev_b32_e32 v218, 16, v63
	v_and_b32_e32 v219, 0xffff0000, v63
	v_lshlrev_b32_e32 v220, 16, v67
	v_and_b32_e32 v221, 0xffff0000, v67
	v_lshlrev_b32_e32 v222, 16, v71
	v_and_b32_e32 v223, 0xffff0000, v71
	v_lshlrev_b32_e32 v224, 16, v99
	v_and_b32_e32 v225, 0xffff0000, v99
	v_lshlrev_b32_e32 v226, 16, v103
	v_and_b32_e32 v227, 0xffff0000, v103
	v_lshlrev_b32_e32 v228, 16, v107
	v_and_b32_e32 v229, 0xffff0000, v107
	v_lshlrev_b32_e32 v230, 16, v111
	v_and_b32_e32 v231, 0xffff0000, v111
	v_pk_mul_f32 v[232:233], v[6:7], v[212:213]
	v_pk_mul_f32 v[234:235], v[6:7], v[214:215]
	v_pk_mul_f32 v[236:237], v[6:7], v[216:217]
	v_pk_mul_f32 v[238:239], v[6:7], v[218:219]
	v_pk_fma_f32 v[232:233], v[14:15], v[214:215], v[232:233]
	v_pk_fma_f32 v[234:235], v[14:15], v[216:217], v[234:235]
	v_pk_fma_f32 v[236:237], v[14:15], v[218:219], v[236:237]
	v_pk_fma_f32 v[238:239], v[14:15], v[220:221], v[238:239]
	v_pk_fma_f32 v[232:233], v[22:23], v[216:217], v[232:233]
	v_pk_fma_f32 v[234:235], v[22:23], v[218:219], v[234:235]
	v_pk_fma_f32 v[236:237], v[22:23], v[220:221], v[236:237]
	v_pk_fma_f32 v[238:239], v[22:23], v[222:223], v[238:239]
	v_pk_mul_f32 v[232:233], v[224:225], v[232:233]
	v_pk_mul_f32 v[234:235], v[226:227], v[234:235]
	v_pk_mul_f32 v[236:237], v[228:229], v[236:237]
	v_pk_mul_f32 v[238:239], v[230:231], v[238:239]
	v_cvt_pk_bf16_f32 v99, v232, v233
	v_cvt_pk_bf16_f32 v103, v234, v235
	v_cvt_pk_bf16_f32 v107, v236, v237
	v_cvt_pk_bf16_f32 v111, v238, v239
	s_waitcnt vmcnt(0)
	v_and_b32_e32 v72, s59, v72
	v_and_b32_e32 v73, s59, v73
	v_and_b32_e32 v74, s59, v74
	v_and_b32_e32 v75, s59, v75
	v_and_b32_e32 v76, s59, v76
	v_and_b32_e32 v77, s59, v77
	v_and_b32_e32 v78, s59, v78
	v_and_b32_e32 v79, s59, v79
	v_lshlrev_b32_e32 v212, 16, v72
	v_and_b32_e32 v213, 0xffff0000, v72
	v_lshlrev_b32_e32 v214, 16, v76
	v_and_b32_e32 v215, 0xffff0000, v76
	v_lshlrev_b32_e32 v216, 16, v80
	v_and_b32_e32 v217, 0xffff0000, v80
	v_lshlrev_b32_e32 v218, 16, v84
	v_and_b32_e32 v219, 0xffff0000, v84
	v_lshlrev_b32_e32 v220, 16, v88
	v_and_b32_e32 v221, 0xffff0000, v88
	v_lshlrev_b32_e32 v222, 16, v92
	v_and_b32_e32 v223, 0xffff0000, v92
	v_lshlrev_b32_e32 v224, 16, v112
	v_and_b32_e32 v225, 0xffff0000, v112
	v_lshlrev_b32_e32 v226, 16, v116
	v_and_b32_e32 v227, 0xffff0000, v116
	v_lshlrev_b32_e32 v228, 16, v120
	v_and_b32_e32 v229, 0xffff0000, v120
	v_lshlrev_b32_e32 v230, 16, v124
	v_and_b32_e32 v231, 0xffff0000, v124
	v_pk_mul_f32 v[232:233], v[24:25], v[212:213]
	v_pk_mul_f32 v[234:235], v[24:25], v[214:215]
	v_pk_mul_f32 v[236:237], v[24:25], v[216:217]
	v_pk_mul_f32 v[238:239], v[24:25], v[218:219]
	v_pk_fma_f32 v[232:233], v[32:33], v[214:215], v[232:233]
	v_pk_fma_f32 v[234:235], v[32:33], v[216:217], v[234:235]
	v_pk_fma_f32 v[236:237], v[32:33], v[218:219], v[236:237]
	v_pk_fma_f32 v[238:239], v[32:33], v[220:221], v[238:239]
	v_pk_fma_f32 v[232:233], v[40:41], v[216:217], v[232:233]
	v_pk_fma_f32 v[234:235], v[40:41], v[218:219], v[234:235]
	v_pk_fma_f32 v[236:237], v[40:41], v[220:221], v[236:237]
	v_pk_fma_f32 v[238:239], v[40:41], v[222:223], v[238:239]
	v_pk_mul_f32 v[232:233], v[224:225], v[232:233]
; __device__ __forceinline__ unsigned cvtpk(float lo, float hi) { unsigned r; asm volatile("v_cvt_pk_bf16_f32 %0, %1, %2" : "=v"(r) : "v"(lo), "v"(hi)); return r; }
; __device__ __forceinline__ void conv_item(const bf16* __restrict__ P, bf16* __restrict__ MIX, const float* __restrict__ cw, int it, int lane) {
;     ...
;     for (int i = 0; i < 4; ++i) { const u32x4 gb = *(const u32x4*)(Pu + (size_t)(t0 + i) * PW + 3072 + c0); float r[8];
; #pragma unroll
;       for (int e = 0; e < 4; ++e) { r[2 * e] = __uint_as_float(gb[e] << 16) * (w0[2 * e] * p[i][2 * e] + w1[2 * e] * p[i + 1][2 * e] + w2[2 * e] * p[i + 2][2 * e]);
;         r[2 * e + 1] = __uint_as_float(gb[e] & 0xffff0000u) * (w0[2 * e + 1] * p[i][2 * e + 1] + w1[2 * e + 1] * p[i + 1][2 * e + 1] + w2[2 * e + 1] * p[i + 2][2 * e + 1]); }
;       u32x4 o; o.x = cvtpk(r[0], r[1]); o.y = cvtpk(r[2], r[3]); o.z = cvtpk(r[4], r[5]); o.w = cvtpk(r[6], r[7]);
;       *(u32x4*)(Mu + (size_t)(t0 + i) * DMODEL + 1024 + c0) = o; } }
	v_pk_mul_f32 v[234:235], v[226:227], v[234:235]
	v_pk_mul_f32 v[236:237], v[228:229], v[236:237]
	v_pk_mul_f32 v[238:239], v[230:231], v[238:239]
	v_cvt_pk_bf16_f32 v112, v232, v233
	v_cvt_pk_bf16_f32 v116, v234, v235
	v_cvt_pk_bf16_f32 v120, v236, v237
	v_cvt_pk_bf16_f32 v124, v238, v239
	v_lshlrev_b32_e32 v212, 16, v73
	v_and_b32_e32 v213, 0xffff0000, v73
	v_lshlrev_b32_e32 v214, 16, v77
	v_and_b32_e32 v215, 0xffff0000, v77
	v_lshlrev_b32_e32 v216, 16, v81
	v_and_b32_e32 v217, 0xffff0000, v81
	v_lshlrev_b32_e32 v218, 16, v85
	v_and_b32_e32 v219, 0xffff0000, v85
	v_lshlrev_b32_e32 v220, 16, v89
	v_and_b32_e32 v221, 0xffff0000, v89
	v_lshlrev_b32_e32 v222, 16, v93
	v_and_b32_e32 v223, 0xffff0000, v93
	v_lshlrev_b32_e32 v224, 16, v113
	v_and_b32_e32 v225, 0xffff0000, v113
	v_lshlrev_b32_e32 v226, 16, v117
	v_and_b32_e32 v227, 0xffff0000, v117
	v_lshlrev_b32_e32 v228, 16, v121
	v_and_b32_e32 v229, 0xffff0000, v121
	v_lshlrev_b32_e32 v230, 16, v125
	v_and_b32_e32 v231, 0xffff0000, v125
	v_pk_mul_f32 v[232:233], v[26:27], v[212:213]
	v_pk_mul_f32 v[234:235], v[26:27], v[214:215]
	v_pk_mul_f32 v[236:237], v[26:27], v[216:217]
	v_pk_mul_f32 v[238:239], v[26:27], v[218:219]
	v_pk_fma_f32 v[232:233], v[34:35], v[214:215], v[232:233]
	v_pk_fma_f32 v[234:235], v[34:35], v[216:217], v[234:235]
	v_pk_fma_f32 v[236:237], v[34:35], v[218:219], v[236:237]
	v_pk_fma_f32 v[238:239], v[34:35], v[220:221], v[238:239]
	v_pk_fma_f32 v[232:233], v[42:43], v[216:217], v[232:233]
	v_pk_fma_f32 v[234:235], v[42:43], v[218:219], v[234:235]
	v_pk_fma_f32 v[236:237], v[42:43], v[220:221], v[236:237]
	v_pk_fma_f32 v[238:239], v[42:43], v[222:223], v[238:239]
	v_pk_mul_f32 v[232:233], v[224:225], v[232:233]
	v_pk_mul_f32 v[234:235], v[226:227], v[234:235]
	v_pk_mul_f32 v[236:237], v[228:229], v[236:237]
	v_pk_mul_f32 v[238:239], v[230:231], v[238:239]
	v_cvt_pk_bf16_f32 v113, v232, v233
	v_cvt_pk_bf16_f32 v117, v234, v235
	v_cvt_pk_bf16_f32 v121, v236, v237
	v_cvt_pk_bf16_f32 v125, v238, v239
	v_lshlrev_b32_e32 v212, 16, v74
	v_and_b32_e32 v213, 0xffff0000, v74
	v_lshlrev_b32_e32 v214, 16, v78
	v_and_b32_e32 v215, 0xffff0000, v78
	v_lshlrev_b32_e32 v216, 16, v82
	v_and_b32_e32 v217, 0xffff0000, v82
	v_lshlrev_b32_e32 v218, 16, v86
	v_and_b32_e32 v219, 0xffff0000, v86
	v_lshlrev_b32_e32 v220, 16, v90
	v_and_b32_e32 v221, 0xffff0000, v90
	v_lshlrev_b32_e32 v222, 16, v94
	v_and_b32_e32 v223, 0xffff0000, v94
	v_lshlrev_b32_e32 v224, 16, v114
	v_and_b32_e32 v225, 0xffff0000, v114
	v_lshlrev_b32_e32 v226, 16, v118
	v_and_b32_e32 v227, 0xffff0000, v118
	v_lshlrev_b32_e32 v228, 16, v122
	v_and_b32_e32 v229, 0xffff0000, v122
	v_lshlrev_b32_e32 v230, 16, v126
	v_and_b32_e32 v231, 0xffff0000, v126
	v_pk_mul_f32 v[232:233], v[28:29], v[212:213]
	v_pk_mul_f32 v[234:235], v[28:29], v[214:215]
	v_pk_mul_f32 v[236:237], v[28:29], v[216:217]
	v_pk_mul_f32 v[238:239], v[28:29], v[218:219]
	v_pk_fma_f32 v[232:233], v[36:37], v[214:215], v[232:233]
	v_pk_fma_f32 v[234:235], v[36:37], v[216:217], v[234:235]
	v_pk_fma_f32 v[236:237], v[36:37], v[218:219], v[236:237]
	v_pk_fma_f32 v[238:239], v[36:37], v[220:221], v[238:239]
	v_pk_fma_f32 v[232:233], v[44:45], v[216:217], v[232:233]
	v_pk_fma_f32 v[234:235], v[44:45], v[218:219], v[234:235]
	v_pk_fma_f32 v[236:237], v[44:45], v[220:221], v[236:237]
	v_pk_fma_f32 v[238:239], v[44:45], v[222:223], v[238:239]
	v_pk_mul_f32 v[232:233], v[224:225], v[232:233]
	v_pk_mul_f32 v[234:235], v[226:227], v[234:235]
	v_pk_mul_f32 v[236:237], v[228:229], v[236:237]
	v_pk_mul_f32 v[238:239], v[230:231], v[238:239]
	v_cvt_pk_bf16_f32 v114, v232, v233
	v_cvt_pk_bf16_f32 v118, v234, v235
	v_cvt_pk_bf16_f32 v122, v236, v237
	v_cvt_pk_bf16_f32 v126, v238, v239
	v_lshlrev_b32_e32 v212, 16, v75
	v_and_b32_e32 v213, 0xffff0000, v75
	v_lshlrev_b32_e32 v214, 16, v79
	v_and_b32_e32 v215, 0xffff0000, v79
	v_lshlrev_b32_e32 v216, 16, v83
	v_and_b32_e32 v217, 0xffff0000, v83
	v_lshlrev_b32_e32 v218, 16, v87
	v_and_b32_e32 v219, 0xffff0000, v87
	v_lshlrev_b32_e32 v220, 16, v91
	v_and_b32_e32 v221, 0xffff0000, v91
	v_lshlrev_b32_e32 v222, 16, v95
	v_and_b32_e32 v223, 0xffff0000, v95
	v_lshlrev_b32_e32 v224, 16, v115
	v_and_b32_e32 v225, 0xffff0000, v115
	v_lshlrev_b32_e32 v226, 16, v119
	v_and_b32_e32 v227, 0xffff0000, v119
	v_lshlrev_b32_e32 v228, 16, v123
	v_and_b32_e32 v229, 0xffff0000, v123
	v_lshlrev_b32_e32 v230, 16, v127
	v_and_b32_e32 v231, 0xffff0000, v127
	v_pk_mul_f32 v[232:233], v[30:31], v[212:213]
	v_pk_mul_f32 v[234:235], v[30:31], v[214:215]
	v_pk_mul_f32 v[236:237], v[30:31], v[216:217]
	v_pk_mul_f32 v[238:239], v[30:31], v[218:219]
	v_pk_fma_f32 v[232:233], v[38:39], v[214:215], v[232:233]
	v_pk_fma_f32 v[234:235], v[38:39], v[216:217], v[234:235]
	v_pk_fma_f32 v[236:237], v[38:39], v[218:219], v[236:237]
	v_pk_fma_f32 v[238:239], v[38:39], v[220:221], v[238:239]
	v_pk_fma_f32 v[232:233], v[46:47], v[216:217], v[232:233]
	v_pk_fma_f32 v[234:235], v[46:47], v[218:219], v[234:235]
	v_pk_fma_f32 v[236:237], v[46:47], v[220:221], v[236:237]
	v_pk_fma_f32 v[238:239], v[46:47], v[222:223], v[238:239]
	v_pk_mul_f32 v[232:233], v[224:225], v[232:233]
	v_pk_mul_f32 v[234:235], v[226:227], v[234:235]
	v_pk_mul_f32 v[236:237], v[228:229], v[236:237]
	v_pk_mul_f32 v[238:239], v[230:231], v[238:239]
	v_cvt_pk_bf16_f32 v115, v232, v233
	v_cvt_pk_bf16_f32 v119, v234, v235
	v_cvt_pk_bf16_f32 v123, v236, v237
	v_cvt_pk_bf16_f32 v127, v238, v239
	global_store_dwordx4 v198, v[96:99], s[0:1] offset:2048
	global_store_dwordx4 v207, v[100:103], s[0:1] offset:2048
	global_store_dwordx4 v208, v[104:107], s[0:1] offset:2048
	global_store_dwordx4 v199, v[108:111], s[0:1] offset:2048
	global_store_dwordx4 v198, v[112:115], s[0:1] offset:3072
	global_store_dwordx4 v207, v[116:119], s[0:1] offset:3072
	global_store_dwordx4 v208, v[120:123], s[0:1] offset:3072
	global_store_dwordx4 v199, v[124:127], s[0:1] offset:3072
